# GEMM1 4th round rebalanced: all 256 WGs run half units (A half only) in a dedicated K-loop with 12 instead of 16 LDS-DMA per iteration; memory k/v projection moved to a small direct-MFMA routine at ph
# baseline (speedup 1.0000x reference)
;     DI bool next(int i, Unit& u) const {
;     ...
;         if (L == 896) { u.pm = 64; u.pn = 79; u.kind = 3; u.om = 0; u.on = 0; return true; }
;         if (L == 897) { u.pm = 80; u.pn = 64; u.kind = 4; u.om = 0; u.on = 0; return true; }
;     DI void operator()(const f32x4 (&acc)[2][2][4][2], const Unit& u, int wr, int wc, int fr, int fq) const {
;     ...
;         else if (u.kind == 3) { base = mk; ldc = 256; }
;         else { base = mvt; ldc = 256; }
.LBB0_124:
	s_mov_b32 s100, 0xff00ff00
	s_mov_b32 s101, 0xff00ff00
	v_bfe_u32 v248, v179, 3, 1
	v_mul_u32_u24_e32 v250, 0x7fc0, v248
	v_sub_u32_e32 v248, 0xffffffc0, v250
	v_mov_b32_e32 v249, -1
	v_sub_u32_e32 v250, 0x7fc0, v250
	v_mov_b32_e32 v251, 0
	v_readfirstlane_b32 s4, v179
	s_lshr_b32 s4, s4, 6
	s_cmp_gt_u32 s4, 1
	s_cbranch_scc1 .Lmk_done
	s_lshl_b32 s5, s2, 1
	s_or_b32 s5, s5, s4
	s_lshr_b32 s8, s5, 8
	s_and_b32 s9, s5, 0xff
	s_lshr_b32 s10, s9, 4
	s_and_b32 s11, s9, 15
	s_lshl_b32 s10, s10, 4
	s_lshl_b32 s11, s11, 4
	s_movk_i32 s12, 0x4000
	s_movk_i32 s13, 0x5000
	s_movk_i32 s16, 0x4f00
	s_cmp_eq_u32 s8, 0
	s_cselect_b32 s17, s12, s13
	s_cselect_b32 s19, s16, s12
	s_add_i32 s17, s17, s10
	s_add_i32 s19, s19, s11
	v_and_b32_e32 v1, 63, v179
	v_and_b32_e32 v2, 15, v1
	v_lshrrev_b32_e32 v3, 4, v1
	v_lshlrev_b32_e32 v3, 4, v3
	v_add_u32_e32 v4, s17, v2
	v_add_u32_e32 v5, s19, v2
	v_lshl_add_u32 v4, v4, 11, v3
	v_lshl_add_u32 v5, v5, 11, v3
	global_load_dwordx4 v[16:19], v4, s[68:69]
	global_load_dwordx4 v[80:83], v5, s[68:69]
	global_load_dwordx4 v[20:23], v4, s[68:69] offset:64
	global_load_dwordx4 v[84:87], v5, s[68:69] offset:64
	global_load_dwordx4 v[24:27], v4, s[68:69] offset:128
	global_load_dwordx4 v[88:91], v5, s[68:69] offset:128
	global_load_dwordx4 v[28:31], v4, s[68:69] offset:192
	global_load_dwordx4 v[92:95], v5, s[68:69] offset:192
	global_load_dwordx4 v[32:35], v4, s[68:69] offset:256
	global_load_dwordx4 v[96:99], v5, s[68:69] offset:256
	global_load_dwordx4 v[36:39], v4, s[68:69] offset:320
	global_load_dwordx4 v[100:103], v5, s[68:69] offset:320
	global_load_dwordx4 v[40:43], v4, s[68:69] offset:384
	global_load_dwordx4 v[104:107], v5, s[68:69] offset:384
	global_load_dwordx4 v[44:47], v4, s[68:69] offset:448
	global_load_dwordx4 v[108:111], v5, s[68:69] offset:448
	global_load_dwordx4 v[48:51], v4, s[68:69] offset:512
	global_load_dwordx4 v[112:115], v5, s[68:69] offset:512
	global_load_dwordx4 v[52:55], v4, s[68:69] offset:576
	global_load_dwordx4 v[116:119], v5, s[68:69] offset:576
	global_load_dwordx4 v[56:59], v4, s[68:69] offset:640
	global_load_dwordx4 v[120:123], v5, s[68:69] offset:640
	global_load_dwordx4 v[60:63], v4, s[68:69] offset:704
	global_load_dwordx4 v[124:127], v5, s[68:69] offset:704
	global_load_dwordx4 v[64:67], v4, s[68:69] offset:768
	global_load_dwordx4 v[128:131], v5, s[68:69] offset:768
	global_load_dwordx4 v[68:71], v4, s[68:69] offset:832
	global_load_dwordx4 v[132:135], v5, s[68:69] offset:832
	global_load_dwordx4 v[72:75], v4, s[68:69] offset:896
	global_load_dwordx4 v[136:139], v5, s[68:69] offset:896
	global_load_dwordx4 v[76:79], v4, s[68:69] offset:960
	global_load_dwordx4 v[140:143], v5, s[68:69] offset:960
	v_mov_b32_e32 v8, 0
	v_mov_b32_e32 v9, 0
	v_mov_b32_e32 v10, 0
	v_mov_b32_e32 v11, 0
	s_lshl_b32 s20, s8, 17
	s_add_u32 s22, s68, 0x9a80000
	s_addc_u32 s23, s69, 0
	s_add_u32 s22, s22, s20
	s_addc_u32 s23, s23, 0
	v_add_u32_e32 v6, s10, v2
	v_lshlrev_b32_e32 v6, 9, v6
	v_lshrrev_b32_e32 v7, 1, v3
	s_lshl_b32 s21, s11, 1
	v_add3_u32 v6, v6, v7, s21
	s_waitcnt vmcnt(30)
	v_mfma_f32_16x16x32_bf16 v[8:11], v[80:83], v[16:19], v[8:11]
	global_load_dwordx4 v[16:19], v4, s[68:69] offset:1024
	global_load_dwordx4 v[80:83], v5, s[68:69] offset:1024
	s_waitcnt vmcnt(30)
	v_mfma_f32_16x16x32_bf16 v[8:11], v[84:87], v[20:23], v[8:11]
	global_load_dwordx4 v[20:23], v4, s[68:69] offset:1088
	global_load_dwordx4 v[84:87], v5, s[68:69] offset:1088
	s_waitcnt vmcnt(30)
	v_mfma_f32_16x16x32_bf16 v[8:11], v[88:91], v[24:27], v[8:11]
	global_load_dwordx4 v[24:27], v4, s[68:69] offset:1152
	global_load_dwordx4 v[88:91], v5, s[68:69] offset:1152
	s_waitcnt vmcnt(30)
	v_mfma_f32_16x16x32_bf16 v[8:11], v[92:95], v[28:31], v[8:11]
	global_load_dwordx4 v[28:31], v4, s[68:69] offset:1216
	global_load_dwordx4 v[92:95], v5, s[68:69] offset:1216
	s_waitcnt vmcnt(30)
;     DI bool next(int i, Unit& u) const {
;     ...
;         if (L == 896) { u.pm = 64; u.pn = 79; u.kind = 3; u.om = 0; u.on = 0; return true; }
;         if (L == 897) { u.pm = 80; u.pn = 64; u.kind = 4; u.om = 0; u.on = 0; return true; }
;     DI void operator()(const f32x4 (&acc)[2][2][4][2], const Unit& u, int wr, int wc, int fr, int fq) const {
;     ...
;                     } else dst = base + (size_t)row * ldc + col;
;                     *(u32x4*)dst = w; } }
	v_mfma_f32_16x16x32_bf16 v[8:11], v[96:99], v[32:35], v[8:11]
	global_load_dwordx4 v[32:35], v4, s[68:69] offset:1280
	global_load_dwordx4 v[96:99], v5, s[68:69] offset:1280
	s_waitcnt vmcnt(30)
	v_mfma_f32_16x16x32_bf16 v[8:11], v[100:103], v[36:39], v[8:11]
	global_load_dwordx4 v[36:39], v4, s[68:69] offset:1344
	global_load_dwordx4 v[100:103], v5, s[68:69] offset:1344
	s_waitcnt vmcnt(30)
	v_mfma_f32_16x16x32_bf16 v[8:11], v[104:107], v[40:43], v[8:11]
	global_load_dwordx4 v[40:43], v4, s[68:69] offset:1408
	global_load_dwordx4 v[104:107], v5, s[68:69] offset:1408
	s_waitcnt vmcnt(30)
	v_mfma_f32_16x16x32_bf16 v[8:11], v[108:111], v[44:47], v[8:11]
	global_load_dwordx4 v[44:47], v4, s[68:69] offset:1472
	global_load_dwordx4 v[108:111], v5, s[68:69] offset:1472
	s_waitcnt vmcnt(30)
	v_mfma_f32_16x16x32_bf16 v[8:11], v[112:115], v[48:51], v[8:11]
	global_load_dwordx4 v[48:51], v4, s[68:69] offset:1536
	global_load_dwordx4 v[112:115], v5, s[68:69] offset:1536
	s_waitcnt vmcnt(30)
	v_mfma_f32_16x16x32_bf16 v[8:11], v[116:119], v[52:55], v[8:11]
	global_load_dwordx4 v[52:55], v4, s[68:69] offset:1600
	global_load_dwordx4 v[116:119], v5, s[68:69] offset:1600
	s_waitcnt vmcnt(30)
	v_mfma_f32_16x16x32_bf16 v[8:11], v[120:123], v[56:59], v[8:11]
	global_load_dwordx4 v[56:59], v4, s[68:69] offset:1664
	global_load_dwordx4 v[120:123], v5, s[68:69] offset:1664
	s_waitcnt vmcnt(30)
	v_mfma_f32_16x16x32_bf16 v[8:11], v[124:127], v[60:63], v[8:11]
	global_load_dwordx4 v[60:63], v4, s[68:69] offset:1728
	global_load_dwordx4 v[124:127], v5, s[68:69] offset:1728
	s_waitcnt vmcnt(30)
	v_mfma_f32_16x16x32_bf16 v[8:11], v[128:131], v[64:67], v[8:11]
	global_load_dwordx4 v[64:67], v4, s[68:69] offset:1792
	global_load_dwordx4 v[128:131], v5, s[68:69] offset:1792
	s_waitcnt vmcnt(30)
	v_mfma_f32_16x16x32_bf16 v[8:11], v[132:135], v[68:71], v[8:11]
	global_load_dwordx4 v[68:71], v4, s[68:69] offset:1856
	global_load_dwordx4 v[132:135], v5, s[68:69] offset:1856
	s_waitcnt vmcnt(30)
	v_mfma_f32_16x16x32_bf16 v[8:11], v[136:139], v[72:75], v[8:11]
	global_load_dwordx4 v[72:75], v4, s[68:69] offset:1920
	global_load_dwordx4 v[136:139], v5, s[68:69] offset:1920
	s_waitcnt vmcnt(30)
	v_mfma_f32_16x16x32_bf16 v[8:11], v[140:143], v[76:79], v[8:11]
	global_load_dwordx4 v[76:79], v4, s[68:69] offset:1984
	global_load_dwordx4 v[140:143], v5, s[68:69] offset:1984
	s_waitcnt vmcnt(30)
	v_mfma_f32_16x16x32_bf16 v[8:11], v[80:83], v[16:19], v[8:11]
	s_waitcnt vmcnt(28)
	v_mfma_f32_16x16x32_bf16 v[8:11], v[84:87], v[20:23], v[8:11]
	s_waitcnt vmcnt(26)
	v_mfma_f32_16x16x32_bf16 v[8:11], v[88:91], v[24:27], v[8:11]
	s_waitcnt vmcnt(24)
	v_mfma_f32_16x16x32_bf16 v[8:11], v[92:95], v[28:31], v[8:11]
	s_waitcnt vmcnt(22)
	v_mfma_f32_16x16x32_bf16 v[8:11], v[96:99], v[32:35], v[8:11]
	s_waitcnt vmcnt(20)
	v_mfma_f32_16x16x32_bf16 v[8:11], v[100:103], v[36:39], v[8:11]
	s_waitcnt vmcnt(18)
	v_mfma_f32_16x16x32_bf16 v[8:11], v[104:107], v[40:43], v[8:11]
	s_waitcnt vmcnt(16)
	v_mfma_f32_16x16x32_bf16 v[8:11], v[108:111], v[44:47], v[8:11]
	s_waitcnt vmcnt(14)
	v_mfma_f32_16x16x32_bf16 v[8:11], v[112:115], v[48:51], v[8:11]
	s_waitcnt vmcnt(12)
	v_mfma_f32_16x16x32_bf16 v[8:11], v[116:119], v[52:55], v[8:11]
	s_waitcnt vmcnt(10)
	v_mfma_f32_16x16x32_bf16 v[8:11], v[120:123], v[56:59], v[8:11]
	s_waitcnt vmcnt(8)
	v_mfma_f32_16x16x32_bf16 v[8:11], v[124:127], v[60:63], v[8:11]
	s_waitcnt vmcnt(6)
	v_mfma_f32_16x16x32_bf16 v[8:11], v[128:131], v[64:67], v[8:11]
	s_waitcnt vmcnt(4)
	v_mfma_f32_16x16x32_bf16 v[8:11], v[132:135], v[68:71], v[8:11]
	s_waitcnt vmcnt(2)
	v_mfma_f32_16x16x32_bf16 v[8:11], v[136:139], v[72:75], v[8:11]
	s_waitcnt vmcnt(0)
	v_mfma_f32_16x16x32_bf16 v[8:11], v[140:143], v[76:79], v[8:11]
	s_nop 15
	v_cvt_pk_bf16_f32 v12, v8, v9
	v_cvt_pk_bf16_f32 v13, v10, v11
	global_store_dwordx2 v6, v[12:13], s[22:23]

;     DI bool next(int i, Unit& u) const {
;         const int L = i * G + c;
;         if (L >= 898) return false;
;         if (L == 896) { u.pm = 64; u.pn = 79; u.kind = 3; u.om = 0; u.on = 0; return true; }
;         if (L == 897) { u.pm = 80; u.pn = 64; u.kind = 4; u.om = 0; u.on = 0; return true; }
;         const int xcd = L & 7, off = L >> 3, wgid = xcd * 112 + off;
;         const int vpm = xcd * 8 + ((wgid % 112) & 7), vpn = (wgid % 112) >> 3;
.LBB0_143:
	s_add_i32 s78, s78, 1
	s_waitcnt lgkmcnt(0)
	s_mul_i32 s25, s78, s33
	s_add_i32 s25, s25, s2
	s_cmp_lg_u32 s78, 3
	s_cbranch_scc1 .Lnot_r4
	s_lshr_b32 s25, s2, 4
	s_lshl_b32 s25, s25, 3
	s_and_b32 s22, s2, 7
	s_or_b32 s25, s25, s22
	s_addk_i32 s25, 0x300
.Lnot_r4:
	s_cmpk_lt_i32 s25, 0x380
	s_cselect_b64 s[20:21], -1, 0
	s_cmpk_gt_i32 s25, 0x37f
	s_cbranch_scc1 .LBB0_158
	s_cmpk_gt_i32 s25, 0x380
	s_mov_b64 s[22:23], -1
	s_cbranch_scc0 .LBB0_146
	s_mov_b64 s[22:23], 0

; template <class Epi, class Sched, bool ALIGN_EPI = false, bool SP2 = true>
; DI void gemm_phase(LAS unsigned char* lds, const Gemm g, const Sched& S, const Epi& E, f32x4 (&acc)[2][2][4][2]) {
;     ...
;         const char* nA = has_next ? (const char*)g.A + (size_t)nxt.pm * tstep : cA; const char* nB = has_next ? (const char*)g.Bt + (size_t)nxt.pn * tstep : cB;
;         for (int t = 0; t < nt; t += 2) {
;             const bool last = (t == nt - 2);
;             const char* a1 = cA + (size_t)(t + 1) * kstep;
;             const char* a2 = last ? nA : cA + (size_t)(t + 2) * kstep; const char* b2 = last ? nB : cB + (size_t)(t + 2) * kstep;
;             const char* a3 = a2 + kstep; const char* b3 = b2 + kstep;
;     ...
;         for (int a = 0; a < 2; ++a)
; #pragma unroll
;             for (int b = 0; b < 2; ++b)
; #pragma unroll
;                 for (int m = 0; m < 4; ++m)
; #pragma unroll
;                     for (int n = 0; n < 2; ++n) acc[a][b][m][n] = (f32x4){0.f, 0.f, 0.f, 0.f};
.LBB0_158:
	s_ashr_i32 s25, s24, 31
	s_lshl_b64 s[26:27], s[24:25], 19
	s_add_u32 s26, s68, s26
	s_addc_u32 s27, s69, s27
	s_cmp_lg_u32 s78, 3
	s_cbranch_scc1 .Lna_done
	s_bitcmp1_b32 s2, 3
	s_cbranch_scc0 .Lna_done
	s_add_u32 s26, s26, 0x40000
	s_addc_u32 s27, s27, 0
.Lna_done:
	s_and_b64 s[28:29], s[20:21], exec
	s_cselect_b32 s25, s27, s1
	s_cselect_b32 s52, s26, s0
	s_ashr_i32 s23, s22, 31
	s_lshl_b64 s[28:29], s[22:23], 19
	s_add_u32 s28, s68, s28
	s_addc_u32 s29, s69, s29
	s_and_b64 s[34:35], s[20:21], exec
	s_cselect_b32 s23, s29, s31
	s_cselect_b32 s53, s28, s30
	s_add_u32 s0, s0, 0x40080
	s_addc_u32 s1, s1, 0
	s_add_u32 s54, s30, 0x100
	v_mov_b32_e32 v0, 0
	s_addc_u32 s55, s31, 0
	s_mov_b32 s62, -2
	v_mov_b32_e32 v1, v0
	v_mov_b32_e32 v2, v0
	v_mov_b32_e32 v3, v0
	v_mov_b32_e32 v4, v0
	v_mov_b32_e32 v5, v0
	v_mov_b32_e32 v6, v0
	v_mov_b32_e32 v7, v0
	v_mov_b32_e32 v16, v0
	v_mov_b32_e32 v17, v0
	v_mov_b32_e32 v18, v0
	v_mov_b32_e32 v19, v0
	v_mov_b32_e32 v20, v0
	v_mov_b32_e32 v21, v0
	v_mov_b32_e32 v22, v0
	v_mov_b32_e32 v23, v0
	v_mov_b32_e32 v32, v0
	v_mov_b32_e32 v33, v0
	v_mov_b32_e32 v34, v0
	v_mov_b32_e32 v35, v0
	v_mov_b32_e32 v36, v0
	v_mov_b32_e32 v37, v0
	v_mov_b32_e32 v38, v0
	v_mov_b32_e32 v39, v0
	v_mov_b32_e32 v48, v0
	v_mov_b32_e32 v49, v0
	v_mov_b32_e32 v50, v0
	v_mov_b32_e32 v51, v0
	v_mov_b32_e32 v52, v0
	v_mov_b32_e32 v53, v0
	v_mov_b32_e32 v54, v0
	v_mov_b32_e32 v55, v0
	v_mov_b32_e32 v8, v0
	v_mov_b32_e32 v9, v0
	v_mov_b32_e32 v10, v0
	v_mov_b32_e32 v11, v0
	v_mov_b32_e32 v12, v0
	v_mov_b32_e32 v13, v0
	v_mov_b32_e32 v14, v0
	v_mov_b32_e32 v15, v0
	v_mov_b32_e32 v24, v0
	v_mov_b32_e32 v25, v0
	v_mov_b32_e32 v26, v0
	v_mov_b32_e32 v27, v0
	v_mov_b32_e32 v28, v0
	v_mov_b32_e32 v29, v0
	v_mov_b32_e32 v30, v0
	v_mov_b32_e32 v31, v0
	v_mov_b32_e32 v40, v0
	v_mov_b32_e32 v41, v0
	v_mov_b32_e32 v42, v0
	v_mov_b32_e32 v43, v0
	v_mov_b32_e32 v44, v0
	v_mov_b32_e32 v45, v0
	v_mov_b32_e32 v46, v0
	v_mov_b32_e32 v47, v0
	v_mov_b32_e32 v56, v0
	v_mov_b32_e32 v57, v0
	v_mov_b32_e32 v58, v0
	v_mov_b32_e32 v59, v0
	v_mov_b32_e32 v60, v0
	v_mov_b32_e32 v61, v0
	v_mov_b32_e32 v62, v0
	v_mov_b32_e32 v63, v0
	v_mov_b32_e32 v64, v0
	v_mov_b32_e32 v65, v0
	v_mov_b32_e32 v66, v0
	v_mov_b32_e32 v67, v0
	v_mov_b32_e32 v68, v0
	v_mov_b32_e32 v69, v0
	v_mov_b32_e32 v70, v0
	v_mov_b32_e32 v71, v0
	v_mov_b32_e32 v80, v0
	v_mov_b32_e32 v81, v0
	v_mov_b32_e32 v82, v0
	v_mov_b32_e32 v83, v0
	v_mov_b32_e32 v84, v0
	v_mov_b32_e32 v85, v0
	v_mov_b32_e32 v86, v0
	v_mov_b32_e32 v87, v0
	v_mov_b32_e32 v96, v0
	v_mov_b32_e32 v97, v0
	v_mov_b32_e32 v98, v0
	v_mov_b32_e32 v99, v0
	v_mov_b32_e32 v100, v0
	v_mov_b32_e32 v101, v0
	v_mov_b32_e32 v102, v0
	v_mov_b32_e32 v103, v0
	v_mov_b32_e32 v112, v0
	v_mov_b32_e32 v113, v0
	v_mov_b32_e32 v114, v0
	v_mov_b32_e32 v115, v0
	v_mov_b32_e32 v116, v0
	v_mov_b32_e32 v117, v0
	v_mov_b32_e32 v118, v0
	v_mov_b32_e32 v119, v0
	v_mov_b32_e32 v72, v0
	v_mov_b32_e32 v73, v0
	v_mov_b32_e32 v74, v0
	v_mov_b32_e32 v75, v0
	v_mov_b32_e32 v76, v0
	v_mov_b32_e32 v77, v0
	v_mov_b32_e32 v78, v0
	v_mov_b32_e32 v79, v0
	v_mov_b32_e32 v88, v0
	v_mov_b32_e32 v89, v0
	v_mov_b32_e32 v90, v0
	v_mov_b32_e32 v91, v0
	v_mov_b32_e32 v92, v0
	v_mov_b32_e32 v93, v0
	v_mov_b32_e32 v94, v0
	v_mov_b32_e32 v95, v0
	v_mov_b32_e32 v104, v0
	v_mov_b32_e32 v105, v0
	v_mov_b32_e32 v106, v0
	v_mov_b32_e32 v107, v0
	v_mov_b32_e32 v108, v0
	v_mov_b32_e32 v109, v0
	v_mov_b32_e32 v110, v0
	v_mov_b32_e32 v111, v0
	v_mov_b32_e32 v120, v0
	v_mov_b32_e32 v121, v0
	v_mov_b32_e32 v122, v0
	v_mov_b32_e32 v123, v0
	v_mov_b32_e32 v124, v0
	v_mov_b32_e32 v125, v0
	v_mov_b32_e32 v126, v0
	v_mov_b32_e32 v127, v0
	s_cmp_eq_u32 s78, 4
	s_cbranch_scc1 .Lhalf_loop

; #define PG8_BAR __builtin_amdgcn_s_barrier()
; template <class Epi, class Sched, bool ALIGN_EPI = false, bool SP2 = true>
; DI void gemm_phase(LAS unsigned char* lds, const Gemm g, const Sched& S, const Epi& E, f32x4 (&acc)[2][2][4][2]) {
;     ...
;         if constexpr (ALIGN_EPI) { if (wr == 0) PG8_BAR; }
;         if constexpr (!Epi::AFTER_DRAIN) { E(acc, cur, wr, wc, fr, fq); }
.Lafter_kloop:
	s_and_b64 vcc, exec, s[16:17]
	s_cbranch_vccz .LBB0_162
	s_barrier

;     DI void operator()(const f32x4 (&acc)[2][2][4][2], const Unit& u, int wr, int wc, int fr, int fq) const {
;     ...
;         const int row0 = u.om * BM + wr * 64 + fr, col0 = u.on * BM + wc * 32 + 8 * fq;
; #pragma unroll
;         for (int ai = 0; ai < 2; ++ai)
; #pragma unroll
;             for (int m = 0; m < 4; ++m) { const int row = row0 + ai * HALF + m * 16;
.LBB0_177:
	s_lshl_b32 s0, s37, 8
	v_lshl_add_u32 v168, s36, 8, v141
	s_cmp_lg_u32 s78, 4
	s_cbranch_scc1 .Lepi_nohalf
	s_bitcmp1_b32 s2, 3
	s_cbranch_scc0 .Lepi_nohalf
	v_add_u32_e32 v168, 0x80, v168
.Lepi_nohalf:
	s_lshl_b32 s36, s79, 1
	s_or_b32 s36, s0, s36
	s_ashr_i32 s34, s37, 1
	s_cmp_lt_u32 s37, 2
	s_cselect_b64 s[0:1], -1, 0
	s_ashr_i32 s35, s34, 31
	s_lshl_b64 s[34:35], s[34:35], 24
	v_ashrrev_i32_e32 v150, 6, v168
	s_add_u32 s34, s30, s34
	v_ashrrev_i32_e32 v151, 31, v150
	s_addc_u32 s35, s31, s35
	v_lshlrev_b64 v[154:155], 2, v[150:151]
	v_or_b32_e32 v154, v154, v138
	s_mov_b64 s[72:73], -1
	s_mov_b64 s[54:55], 0
	s_cmp_lt_i32 s38, 1
	s_mov_b64 s[62:63], 0
	s_cbranch_scc1 .LBB0_181
	s_cmp_eq_u32 s38, 1
	s_mov_b64 s[62:63], -1
	s_cbranch_scc0 .LBB0_180
	s_ashr_i32 s62, s36, 5
	s_ashr_i32 s63, s62, 31
	s_lshl_b64 s[62:63], s[62:63], 11
	v_lshlrev_b64 v[150:151], 6, v[154:155]
	v_lshl_add_u64 v[150:151], v[150:151], 0, s[62:63]
	v_or_b32_e32 v150, v150, v142
	v_lshl_add_u64 v[160:161], v[150:151], 4, s[30:31]
	s_mov_b64 s[62:63], 0

;     DI void operator()(const f32x4 (&acc)[2][2][4][2], const Unit& u, int wr, int wc, int fr, int fq) const {
;     ...
; #pragma unroll
;         for (int ai = 0; ai < 2; ++ai)
; #pragma unroll
;             for (int m = 0; m < 4; ++m) { const int row = row0 + ai * HALF + m * 16;
; #pragma unroll
;                 for (int bj = 0; bj < 2; ++bj) { const f32x4 v0 = acc[ai][bj][m][0] * sc, v1 = acc[ai][bj][m][1] * sc; const int col = col0 + bj * HALF;
.Lk2d_3:
	s_cmp_eq_u32 s78, 4
	s_cbranch_scc1 .Lepi_half_end
	s_mov_b64 s[72:73], -1
	s_mov_b64 s[54:55], 0
	v_ashrrev_i32_e32 v64, 6, v68
	v_ashrrev_i32_e32 v65, 31, v64
	v_lshlrev_b64 v[64:65], 2, v[64:65]
	v_or_b32_e32 v64, v64, v138
	s_cmp_lt_i32 s38, 1
	s_mov_b64 s[62:63], 0
	s_cbranch_scc1 .LBB0_241
	s_cmp_eq_u32 s38, 1
	s_mov_b64 s[62:63], -1
	s_cbranch_scc0 .LBB0_240
	s_ashr_i32 s62, s36, 5
	s_ashr_i32 s63, s62, 31
	s_lshl_b64 s[62:63], s[62:63], 11
	v_lshlrev_b64 v[66:67], 6, v[64:65]
	v_lshl_add_u64 v[66:67], v[66:67], 0, s[62:63]
	v_or_b32_e32 v66, v66, v142
	v_lshl_add_u64 v[70:71], v[66:67], 4, s[30:31]
	s_mov_b64 s[62:63], 0

; #define PG8_BAR __builtin_amdgcn_s_barrier()
; template <class Epi, class Sched, bool ALIGN_EPI = false, bool SP2 = true>
; DI void gemm_phase(LAS unsigned char* lds, const Gemm g, const Sched& S, const Epi& E, f32x4 (&acc)[2][2][4][2]) {
;     ...
;         if (!has_next) break;
; #pragma unroll
;         for (int a = 0; a < 2; ++a)
; #pragma unroll
;             for (int b = 0; b < 2; ++b)
; #pragma unroll
;                 for (int m = 0; m < 4; ++m)
; #pragma unroll
;                     for (int n = 0; n < 2; ++n) acc[a][b][m][n] = (f32x4){0.f, 0.f, 0.f, 0.f};
;         cur = nxt; cA = nA; cB = nB; ++ui;
;         if constexpr (ALIGN_EPI) { if (wr == 1) PG8_BAR; }
.Lepi_after:
	s_andn2_b64 vcc, exec, s[12:13]
	s_cbranch_vccnz .LBB0_141
	s_barrier
	s_branch .LBB0_141
.Lepi_half_end:
	s_andn2_b64 vcc, exec, s[20:21]
	s_mov_b64 s[0:1], -1
	s_cbranch_vccnz .LBB0_142
	s_branch .Lepi_after

; #define PG8_STAGE(bufoff, gbase, voff) do { _Pragma("unroll") for (int _i = 0; _i < 2; ++_i) \
;         __builtin_amdgcn_global_load_lds((const unsigned*)((const char*)(gbase) + (voff)[_i]), (LAS unsigned*)(lds + (bufoff) + ldsw + _i * 8192), 16, 0, 0); } while (0)
; #define PG8_LDA(dst, b, h) do { _Pragma("unroll") for (int m = 0; m < 4; ++m) _Pragma("unroll") for (int k = 0; k < 2; ++k) dst[m][k] = *(const LAS bf16x8*)(lds + PG8_SA(b, h) + aoff + m * 2048 + k * 1024); } while (0)
; #define PG8_LDB(dst, b, h) do { _Pragma("unroll") for (int n = 0; n < 2; ++n) _Pragma("unroll") for (int k = 0; k < 2; ++k) dst[n][k] = *(const LAS bf16x8*)(lds + PG8_SB(b, h) + boff + n * 2048 + k * 1024); } while (0)
; #define PG8_MMA(ai, bj, At, Bt) do { __builtin_amdgcn_s_setprio(1); _Pragma("unroll") for (int m = 0; m < 4; ++m) _Pragma("unroll") for (int n = 0; n < 2; ++n) _Pragma("unroll") for (int k = 0; k < 2; ++k) \
;         acc[ai][bj][m][n] = __builtin_amdgcn_mfma_f32_16x16x32_bf16(Bt[n][k], At[m][k], acc[ai][bj][m][n], 0, 0, 0); __builtin_amdgcn_s_setprio(0); } while (0)
; #define PG8_WAIT_V(n) asm volatile("s_waitcnt vmcnt(" #n ")" ::: "memory")
; template <class Epi, class Sched, bool ALIGN_EPI = false, bool SP2 = true>
; DI void gemm_phase(LAS unsigned char* lds, const Gemm g, const Sched& S, const Epi& E, f32x4 (&acc)[2][2][4][2]) {
;     ...
;             PG8_LDB(B0, 0, 0); PG8_LDB(B1, 0, 1); PG8_SCHED; PG8_LDA(At, 0, 0); PG8_STAGE(PG8_SA(1, 1), a1 + hstep, voffA);
;             PG8_WAIT_V(8); PG8_WAIT_L(0); PG8_BAR; PG8_MMA(0, 0, At, B0); PG8_MMA(0, 1, At, B1); PG8_BAR; PG8_SCHED;
;             PG8_LDA(At, 0, 1); PG8_STAGE(PG8_SB(0, 0), b2, voffB); PG8_STAGE(PG8_SB(0, 1), b2 + hstep, voffB); PG8_STAGE(PG8_SA(0, 0), a2, voffA);
;             PG8_WAIT_V(8); PG8_WAIT_L(0); PG8_BAR; PG8_MMA(1, 0, At, B0); PG8_MMA(1, 1, At, B1); PG8_BAR; PG8_SCHED;
;             PG8_LDB(B0, 1, 0); PG8_LDB(B1, 1, 1); PG8_SCHED; PG8_LDA(At, 1, 0); PG8_STAGE(PG8_SA(0, 1), a2 + hstep, voffA);
;             PG8_WAIT_V(8); PG8_WAIT_L(0); PG8_BAR; PG8_MMA(0, 0, At, B0); PG8_MMA(0, 1, At, B1); PG8_BAR; PG8_SCHED;
;             PG8_LDA(At, 1, 1); PG8_STAGE(PG8_SB(1, 0), b3, voffB); PG8_STAGE(PG8_SB(1, 1), b3 + hstep, voffB); PG8_STAGE(PG8_SA(1, 0), a3, voffA);
;             PG8_WAIT_V(8); PG8_WAIT_L(0); PG8_BAR; PG8_MMA(1, 0, At, B0); PG8_MMA(1, 1, At, B1); PG8_BAR; PG8_SCHED;
.Lhalf_loop:
	ds_read_b128 v[150:153], v164
	ds_read_b128 v[154:157], v164 offset:1024
	ds_read_b128 v[158:161], v164 offset:2048
	ds_read_b128 v[168:171], v164 offset:3072
	ds_read_b128 v[172:175], v165
	ds_read_b128 v[180:183], v165 offset:1024
	ds_read_b128 v[184:187], v165 offset:2048
	ds_read_b128 v[188:191], v165 offset:3072
	s_add_u32 s30, s0, 0xfffc0080
	s_addc_u32 s31, s1, -1
	s_cmp_eq_u32 s62, 12
	s_cselect_b32 s35, s25, s31
	s_cselect_b32 s34, s52, s30
	s_cselect_b32 s31, s23, s55
	s_cselect_b32 s30, s53, s54
	v_lshl_add_u64 v[176:177], s[0:1], 0, v[146:147]
	s_add_i32 m0, s74, 0xc000
	ds_read_b128 v[192:195], v166
	ds_read_b128 v[196:199], v166 offset:1024
	ds_read_b128 v[202:205], v166 offset:2048
	ds_read_b128 v[206:209], v166 offset:3072
	ds_read_b128 v[210:213], v166 offset:4096
	ds_read_b128 v[214:217], v166 offset:5120
	ds_read_b128 v[218:221], v166 offset:6144
	ds_read_b128 v[222:225], v166 offset:7168
	v_lshl_add_u64 v[176:177], s[0:1], 0, v[148:149]
	s_add_i32 m0, s74, 0xe000
	s_nop 0
	s_waitcnt vmcnt(6)
	s_waitcnt lgkmcnt(0)
	s_barrier
	s_setprio 1
	s_waitcnt lgkmcnt(0)
	v_mfma_f32_16x16x32_bf16 v[124:127], v[150:153], v[192:195], v[124:127]
	v_mfma_f32_16x16x32_bf16 v[120:123], v[158:161], v[192:195], v[120:123]
	v_mfma_f32_16x16x32_bf16 v[108:111], v[150:153], v[202:205], v[108:111]
	v_mfma_f32_16x16x32_bf16 v[104:107], v[158:161], v[202:205], v[104:107]
	v_mfma_f32_16x16x32_bf16 v[92:95], v[150:153], v[210:213], v[92:95]
	v_mfma_f32_16x16x32_bf16 v[88:91], v[158:161], v[210:213], v[88:91]
	v_mfma_f32_16x16x32_bf16 v[76:79], v[150:153], v[218:221], v[76:79]
	v_mfma_f32_16x16x32_bf16 v[72:75], v[158:161], v[218:221], v[72:75]
	v_mfma_f32_16x16x32_bf16 v[124:127], v[154:157], v[196:199], v[124:127]
	v_mfma_f32_16x16x32_bf16 v[120:123], v[168:171], v[196:199], v[120:123]
	v_mfma_f32_16x16x32_bf16 v[108:111], v[154:157], v[206:209], v[108:111]
	v_mfma_f32_16x16x32_bf16 v[104:107], v[168:171], v[206:209], v[104:107]
	v_mfma_f32_16x16x32_bf16 v[92:95], v[154:157], v[214:217], v[92:95]
	v_mfma_f32_16x16x32_bf16 v[88:91], v[168:171], v[214:217], v[88:91]
	v_mfma_f32_16x16x32_bf16 v[76:79], v[154:157], v[222:225], v[76:79]
	v_mfma_f32_16x16x32_bf16 v[72:75], v[168:171], v[222:225], v[72:75]
	s_setprio 0
	s_setprio 1
	v_mfma_f32_16x16x32_bf16 v[116:119], v[172:175], v[192:195], v[116:119]
	v_mfma_f32_16x16x32_bf16 v[112:115], v[184:187], v[192:195], v[112:115]
	v_mfma_f32_16x16x32_bf16 v[100:103], v[172:175], v[202:205], v[100:103]
	v_mfma_f32_16x16x32_bf16 v[96:99], v[184:187], v[202:205], v[96:99]
	v_mfma_f32_16x16x32_bf16 v[84:87], v[172:175], v[210:213], v[84:87]
	v_mfma_f32_16x16x32_bf16 v[80:83], v[184:187], v[210:213], v[80:83]
	v_mfma_f32_16x16x32_bf16 v[68:71], v[172:175], v[218:221], v[68:71]
	v_mfma_f32_16x16x32_bf16 v[64:67], v[184:187], v[218:221], v[64:67]
	v_mfma_f32_16x16x32_bf16 v[116:119], v[180:183], v[196:199], v[116:119]
	v_mfma_f32_16x16x32_bf16 v[112:115], v[188:191], v[196:199], v[112:115]
	v_mfma_f32_16x16x32_bf16 v[100:103], v[180:183], v[206:209], v[100:103]
	v_mfma_f32_16x16x32_bf16 v[96:99], v[188:191], v[206:209], v[96:99]
	v_mfma_f32_16x16x32_bf16 v[84:87], v[180:183], v[214:217], v[84:87]
	v_mfma_f32_16x16x32_bf16 v[80:83], v[188:191], v[214:217], v[80:83]
	v_mfma_f32_16x16x32_bf16 v[68:71], v[180:183], v[222:225], v[68:71]
	v_mfma_f32_16x16x32_bf16 v[64:67], v[188:191], v[222:225], v[64:67]
	s_setprio 0
	s_barrier
	s_add_i32 s63, s82, s39
	v_lshl_add_u64 v[176:177], s[30:31], 0, v[130:131]
	s_mov_b32 m0, s63
	global_load_lds_dwordx4 v[176:177], off
	s_add_i32 m0, s63, 0x2000
	s_add_u32 s72, s30, 0x10000
	v_lshl_add_u64 v[226:227], s[30:31], 0, v[134:135]
	s_addc_u32 s73, s31, 0
	s_add_i32 s63, s83, s39
	global_load_lds_dwordx4 v[226:227], off
	v_lshl_add_u64 v[228:229], s[72:73], 0, v[130:131]
	s_mov_b32 m0, s63
	v_lshl_add_u64 v[230:231], s[34:35], 0, v[132:133]
	global_load_lds_dwordx4 v[228:229], off
	v_lshl_add_u64 v[228:229], s[72:73], 0, v[134:135]
	s_add_i32 m0, s63, 0x2000
	s_nop 0
	global_load_lds_dwordx4 v[228:229], off
	v_lshl_add_u64 v[228:229], s[34:35], 0, v[128:129]
	s_mov_b32 m0, s74
	s_nop 0
	global_load_lds_dwordx4 v[228:229], off
	s_mov_b32 m0, s75
	s_nop 0
	global_load_lds_dwordx4 v[230:231], off
	s_waitcnt vmcnt(6)
	s_waitcnt lgkmcnt(0)
	s_barrier
	s_setprio 1
	s_waitcnt lgkmcnt(0)
	s_setprio 0
	s_setprio 1
	s_setprio 0
	s_barrier
; #define PG8_STAGE(bufoff, gbase, voff) do { _Pragma("unroll") for (int _i = 0; _i < 2; ++_i) \
;         __builtin_amdgcn_global_load_lds((const unsigned*)((const char*)(gbase) + (voff)[_i]), (LAS unsigned*)(lds + (bufoff) + ldsw + _i * 8192), 16, 0, 0); } while (0)
; #define PG8_LDA(dst, b, h) do { _Pragma("unroll") for (int m = 0; m < 4; ++m) _Pragma("unroll") for (int k = 0; k < 2; ++k) dst[m][k] = *(const LAS bf16x8*)(lds + PG8_SA(b, h) + aoff + m * 2048 + k * 1024); } while (0)
; #define PG8_LDB(dst, b, h) do { _Pragma("unroll") for (int n = 0; n < 2; ++n) _Pragma("unroll") for (int k = 0; k < 2; ++k) dst[n][k] = *(const LAS bf16x8*)(lds + PG8_SB(b, h) + boff + n * 2048 + k * 1024); } while (0)
; #define PG8_MMA(ai, bj, At, Bt) do { __builtin_amdgcn_s_setprio(1); _Pragma("unroll") for (int m = 0; m < 4; ++m) _Pragma("unroll") for (int n = 0; n < 2; ++n) _Pragma("unroll") for (int k = 0; k < 2; ++k) \
;         acc[ai][bj][m][n] = __builtin_amdgcn_mfma_f32_16x16x32_bf16(Bt[n][k], At[m][k], acc[ai][bj][m][n], 0, 0, 0); __builtin_amdgcn_s_setprio(0); } while (0)
; #define PG8_WAIT_V(n) asm volatile("s_waitcnt vmcnt(" #n ")" ::: "memory")
; #define PG8_WAIT_L(n) asm volatile("s_waitcnt lgkmcnt(" #n ")" ::: "memory")
; #define PG8_BAR __builtin_amdgcn_s_barrier()
; #define PG8_SCHED __builtin_amdgcn_sched_barrier(0)
; template <class Epi, class Sched, bool ALIGN_EPI = false, bool SP2 = true>
; DI void gemm_phase(LAS unsigned char* lds, const Gemm g, const Sched& S, const Epi& E, f32x4 (&acc)[2][2][4][2]) {
;     ...
;             PG8_LDB(B0, 1, 0); PG8_LDB(B1, 1, 1); PG8_SCHED; PG8_LDA(At, 1, 0); PG8_STAGE(PG8_SA(0, 1), a2 + hstep, voffA);
;             PG8_WAIT_V(8); PG8_WAIT_L(0); PG8_BAR; PG8_MMA(0, 0, At, B0); PG8_MMA(0, 1, At, B1); PG8_BAR; PG8_SCHED;
;             PG8_LDA(At, 1, 1); PG8_STAGE(PG8_SB(1, 0), b3, voffB); PG8_STAGE(PG8_SB(1, 1), b3 + hstep, voffB); PG8_STAGE(PG8_SA(1, 0), a3, voffA);
;             PG8_WAIT_V(8); PG8_WAIT_L(0); PG8_BAR; PG8_MMA(1, 0, At, B0); PG8_MMA(1, 1, At, B1); PG8_BAR; PG8_SCHED;
	s_add_i32 s63, 0, 0x18000
	s_add_i32 s64, 0, 0x1c000
	v_add_u32_e32 v168, s63, v143
	v_add_u32_e32 v178, s64, v143
	ds_read_b128 v[150:153], v168
	ds_read_b128 v[154:157], v168 offset:1024
	ds_read_b128 v[158:161], v168 offset:2048
	ds_read_b128 v[168:171], v168 offset:3072
	ds_read_b128 v[172:175], v178
	ds_read_b128 v[180:183], v178 offset:1024
	ds_read_b128 v[184:187], v178 offset:2048
	ds_read_b128 v[188:191], v178 offset:3072
	s_add_u32 s34, s34, 0x40000
	s_addc_u32 s35, s35, 0
	s_mov_b32 m0, s76
	v_lshl_add_u64 v[232:233], s[34:35], 0, v[128:129]
	ds_read_b128 v[192:195], v166 offset:32768
	ds_read_b128 v[196:199], v166 offset:33792
	ds_read_b128 v[202:205], v166 offset:34816
	ds_read_b128 v[206:209], v166 offset:35840
	ds_read_b128 v[210:213], v166 offset:36864
	ds_read_b128 v[214:217], v166 offset:37888
	ds_read_b128 v[218:221], v166 offset:38912
	ds_read_b128 v[222:225], v166 offset:39936
	v_lshl_add_u64 v[232:233], s[34:35], 0, v[132:133]
	s_mov_b32 m0, s77
	s_nop 0
	s_waitcnt vmcnt(6)
	s_waitcnt lgkmcnt(0)
	s_barrier
	s_setprio 1
	s_waitcnt lgkmcnt(0)
	v_mfma_f32_16x16x32_bf16 v[124:127], v[150:153], v[192:195], v[124:127]
	v_mfma_f32_16x16x32_bf16 v[120:123], v[158:161], v[192:195], v[120:123]
	v_mfma_f32_16x16x32_bf16 v[108:111], v[150:153], v[202:205], v[108:111]
	v_mfma_f32_16x16x32_bf16 v[104:107], v[158:161], v[202:205], v[104:107]
	v_mfma_f32_16x16x32_bf16 v[92:95], v[150:153], v[210:213], v[92:95]
	v_mfma_f32_16x16x32_bf16 v[88:91], v[158:161], v[210:213], v[88:91]
	v_mfma_f32_16x16x32_bf16 v[76:79], v[150:153], v[218:221], v[76:79]
	v_mfma_f32_16x16x32_bf16 v[72:75], v[158:161], v[218:221], v[72:75]
	v_mfma_f32_16x16x32_bf16 v[124:127], v[154:157], v[196:199], v[124:127]
	v_mfma_f32_16x16x32_bf16 v[120:123], v[168:171], v[196:199], v[120:123]
	v_mfma_f32_16x16x32_bf16 v[108:111], v[154:157], v[206:209], v[108:111]
	v_mfma_f32_16x16x32_bf16 v[104:107], v[168:171], v[206:209], v[104:107]
	v_mfma_f32_16x16x32_bf16 v[92:95], v[154:157], v[214:217], v[92:95]
	v_mfma_f32_16x16x32_bf16 v[88:91], v[168:171], v[214:217], v[88:91]
	v_mfma_f32_16x16x32_bf16 v[76:79], v[154:157], v[222:225], v[76:79]
	v_mfma_f32_16x16x32_bf16 v[72:75], v[168:171], v[222:225], v[72:75]
	s_setprio 0
	s_setprio 1
	v_mfma_f32_16x16x32_bf16 v[116:119], v[172:175], v[192:195], v[116:119]
	v_mfma_f32_16x16x32_bf16 v[112:115], v[184:187], v[192:195], v[112:115]
	v_mfma_f32_16x16x32_bf16 v[100:103], v[172:175], v[202:205], v[100:103]
	v_mfma_f32_16x16x32_bf16 v[96:99], v[184:187], v[202:205], v[96:99]
	v_mfma_f32_16x16x32_bf16 v[84:87], v[172:175], v[210:213], v[84:87]
	v_mfma_f32_16x16x32_bf16 v[80:83], v[184:187], v[210:213], v[80:83]
	v_mfma_f32_16x16x32_bf16 v[68:71], v[172:175], v[218:221], v[68:71]
	v_mfma_f32_16x16x32_bf16 v[64:67], v[184:187], v[218:221], v[64:67]
	v_mfma_f32_16x16x32_bf16 v[116:119], v[180:183], v[196:199], v[116:119]
	v_mfma_f32_16x16x32_bf16 v[112:115], v[188:191], v[196:199], v[112:115]
	v_mfma_f32_16x16x32_bf16 v[100:103], v[180:183], v[206:209], v[100:103]
	v_mfma_f32_16x16x32_bf16 v[96:99], v[188:191], v[206:209], v[96:99]
	v_mfma_f32_16x16x32_bf16 v[84:87], v[180:183], v[214:217], v[84:87]
	v_mfma_f32_16x16x32_bf16 v[80:83], v[188:191], v[214:217], v[80:83]
	v_mfma_f32_16x16x32_bf16 v[68:71], v[180:183], v[222:225], v[68:71]
	v_mfma_f32_16x16x32_bf16 v[64:67], v[188:191], v[222:225], v[64:67]
	s_setprio 0
	s_barrier
	s_add_i32 s34, s63, s39
	v_lshl_add_u64 v[176:177], v[176:177], 0, s[14:15]
	s_mov_b32 m0, s34
	global_load_lds_dwordx4 v[176:177], off
	s_add_i32 m0, s34, 0x2000
	s_add_u32 s30, s30, 0x10080
	v_lshl_add_u64 v[176:177], v[226:227], 0, s[14:15]
	s_addc_u32 s31, s31, 0
	s_add_i32 s34, s64, s39
	global_load_lds_dwordx4 v[176:177], off
	v_lshl_add_u64 v[176:177], s[30:31], 0, v[130:131]
	s_mov_b32 m0, s34
	s_nop 0
	global_load_lds_dwordx4 v[176:177], off
	v_lshl_add_u64 v[176:177], s[30:31], 0, v[134:135]
	s_add_i32 m0, s34, 0x2000
	s_nop 0
	global_load_lds_dwordx4 v[176:177], off
	v_lshl_add_u64 v[176:177], v[228:229], 0, s[14:15]
	s_mov_b32 m0, s80
	s_nop 0
	global_load_lds_dwordx4 v[176:177], off
	v_lshl_add_u64 v[176:177], v[230:231], 0, s[14:15]
	s_mov_b32 m0, s81
	s_nop 0
	global_load_lds_dwordx4 v[176:177], off
	s_waitcnt vmcnt(6)
	s_waitcnt lgkmcnt(0)
	s_barrier
	s_setprio 1
	s_waitcnt lgkmcnt(0)
	s_setprio 0
	s_setprio 1
	s_setprio 0
	s_barrier
	s_add_i32 s62, s62, 2
	s_add_u32 s0, s0, 0x100
	s_addc_u32 s1, s1, 0
	s_add_u32 s54, s54, 0x100
	s_addc_u32 s55, s55, 0
	s_cmp_gt_u32 s62, 13
	s_cbranch_scc0 .Lhalf_loop

; template <class Epi, class Sched, bool ALIGN_EPI = false, bool SP2 = true>
; DI void gemm_phase(LAS unsigned char* lds, const Gemm g, const Sched& S, const Epi& E, f32x4 (&acc)[2][2][4][2]) {
;     ...
;         for (int t = 0; t < nt; t += 2) {
;             const bool last = (t == nt - 2);
;             const char* a1 = cA + (size_t)(t + 1) * kstep;
;             const char* a2 = last ? nA : cA + (size_t)(t + 2) * kstep; const char* b2 = last ? nB : cB + (size_t)(t + 2) * kstep;
;             const char* a3 = a2 + kstep; const char* b3 = b2 + kstep;
;             if constexpr (SP2) {
;             PG8_LDB(B0, 0, 0); PG8_LDB(B1, 0, 1); PG8_SCHED; PG8_LDA(At, 0, 0); PG8_STAGE(PG8_SA(1, 1), a1 + hstep, voffA);
;             PG8_WAIT_V(8); PG8_WAIT_L(0); PG8_BAR; PG8_MMA(0, 0, At, B0); PG8_MMA(0, 1, At, B1); PG8_BAR; PG8_SCHED;
;             PG8_LDA(At, 0, 1); PG8_STAGE(PG8_SB(0, 0), b2, voffB); PG8_STAGE(PG8_SB(0, 1), b2 + hstep, voffB); PG8_STAGE(PG8_SA(0, 0), a2, voffA);
;             PG8_WAIT_V(8); PG8_WAIT_L(0); PG8_BAR; PG8_MMA(1, 0, At, B0); PG8_MMA(1, 1, At, B1); PG8_BAR; PG8_SCHED;
;             PG8_LDB(B0, 1, 0); PG8_LDB(B1, 1, 1); PG8_SCHED; PG8_LDA(At, 1, 0); PG8_STAGE(PG8_SA(0, 1), a2 + hstep, voffA);
;             PG8_WAIT_V(8); PG8_WAIT_L(0); PG8_BAR; PG8_MMA(0, 0, At, B0); PG8_MMA(0, 1, At, B1); PG8_BAR; PG8_SCHED;
;             PG8_LDA(At, 1, 1); PG8_STAGE(PG8_SB(1, 0), b3, voffB); PG8_STAGE(PG8_SB(1, 1), b3 + hstep, voffB); PG8_STAGE(PG8_SA(1, 0), a3, voffA);
;             PG8_WAIT_V(8); PG8_WAIT_L(0); PG8_BAR; PG8_MMA(1, 0, At, B0); PG8_MMA(1, 1, At, B1); PG8_BAR; PG8_SCHED;
;             } else {
;             PG8_LDB(B0, 0, 0); PG8_SCHED; PG8_LDA(At, 0, 0); PG8_STAGE(PG8_SA(1, 1), a1 + hstep, voffA);
;             PG8_WAIT_L(8); PG8_BAR; PG8_WAIT_L(0); PG8_MMA(0, 0, At, B0); PG8_BAR; PG8_SCHED;
;             PG8_LDB(B1, 0, 1); PG8_STAGE(PG8_SB(0, 0), b2, voffB);
;             PG8_BAR; PG8_WAIT_L(0); PG8_MMA(0, 1, At, B1); PG8_BAR;
;             PG8_LDA(At, 0, 1); PG8_STAGE(PG8_SA(0, 0), a2, voffA);
;             PG8_BAR; PG8_WAIT_L(0); PG8_MMA(1, 0, At, B0); PG8_BAR; PG8_SCHED;
;             PG8_STAGE(PG8_SB(0, 1), b2 + hstep, voffB);
;             PG8_WAIT_V(6); PG8_BAR; PG8_MMA(1, 1, At, B1); PG8_BAR;
;             PG8_LDB(B0, 1, 0); PG8_SCHED; PG8_LDA(At, 1, 0); PG8_STAGE(PG8_SA(0, 1), a2 + hstep, voffA);
	s_branch .Lafter_kloop
